# sliding-window tile loop: tile-range test (scalar shifts and compares) moved above the per-tile barrier
# speedup vs baseline: 1.0061x; 1.0012x over previous
; template <int BR>
; DI void attn_branch(const AttnCtx& c, unsigned long long tmask, const bf16_t* kbase, size_t kpitch, const bf16_t* vbase, size_t vpitch, f32x16 (&o)[2], float& lsum) {
;     ...
;             const float sbias = (BR == 2 && !mine) ? -1e30f : 0.f;
;             bool interior;
;             if (BR <= 1) interior = jc * 64 + 64 <= c.ncvmin;
;             else if (BR == 2) interior = jc * 64 + 63 <= c.tw;
;             else interior = (jc * 64 + 63 <= c.tw) && (jc * 64 > c.tw + 31 - 512);
.LBB0_395:
	s_lshl_b32 s12, s8, 6
	s_or_b32 s13, s12, 63
	v_cmp_gt_i32_e32 vcc, s13, v171
	v_cmp_le_i32_e64 s[0:1], s12, v177
	s_or_b64 s[0:1], vcc, s[0:1]
	s_waitcnt lgkmcnt(0)
	s_barrier
	s_and_saveexec_b64 s[8:9], s[0:1]
	s_xor_b64 s[8:9], exec, s[8:9]
	s_cbranch_execnz .LBB0_398
	s_andn2_saveexec_b64 s[0:1], s[8:9]
	s_cbranch_execnz .LBB0_403
